# attention: p0 exps moved behind the mid-body barrier so the next K-fragment reads fly under them
# speedup vs baseline: 1.0006x; 1.0006x over previous
; #define SBAR() __builtin_amdgcn_sched_barrier(0)
; #define SLOAD(i, k0) do { sr_[i].vs0 = St::ld8(&Vh[(long)((k0) + sr) * LDK + sc]); sr_[i].vs1 = St::ld8(&Vh[(long)((k0) + 32 + sr) * LDK + sc]); \
;     sr_[i].ks0 = St::ld8(&Kh[(long)((k0) + sr) * LDK + sc]); sr_[i].ks1 = St::ld8(&Kh[(long)((k0) + 32 + sr) * LDK + sc]); } while (0)
; #define RESC(a) do { if (__any((a) < 1.f)) { if (hi == 0) al_l[r32] = (a); asm volatile("s_waitcnt lgkmcnt(0)" ::: "memory"); \
;     for (int d = 0; d < 4; ++d) for (int r = 0; r < 16; ++r) o[d][r] *= al_l[crow(r, hi)]; } } while (0)
; __device__ __forceinline__ void partialSM(f32x16& p0, f32x16& p1, float& m_reg, float& mn, float& alpha) {
;     ...
;   float mnC = -mn * C;
;   for (int r = 0; r < 16; ++r) p0[r] = fmaf(p0[r], C, mnC); for (int r = 0; r < 16; ++r) p1[r] = fmaf(p1[r], C, mnC);
;   for (int r = 0; r < 16; ++r) p0[r] = __builtin_amdgcn_exp2f(p0[r]);
; }
; __device__ __forceinline__ void finishSM(f32x16& p0, f32x16& p1, float alpha, float& l_reg, bf16x8& pa0, bf16x8& pa1, bf16x8& pa2, bf16x8& pa3) {
;   for (int r = 0; r < 16; ++r) p1[r] = __builtin_amdgcn_exp2f(p1[r]);
;   float ps = 0; for (int r = 0; r < 16; ++r) ps += p0[r]; for (int r = 0; r < 16; ++r) ps += p1[r];
;   { auto rr = __builtin_amdgcn_permlane32_swap(__float_as_uint(ps), __float_as_uint(ps), false, false);
;     ps = __uint_as_float(rr[0]) + __uint_as_float(rr[1]); }
;   l_reg = l_reg * alpha + ps;
;     ...
;   PK4(p0, 0, pa0); PK4(p0, 8, pa1); PK4(p1, 0, pa2); PK4(p1, 8, pa3);
; template <typename TQ>
; __device__ __forceinline__ void attn_dense_body(const TQ* __restrict__ Qb, const bf16* __restrict__ Kh, const bf16* __restrict__ Vh,
;                                                 unsigned short* __restrict__ Ob, int seq, char* lds, const int wave_s) {
;     ...
;     RESC(alB); __syncthreads();
;     SBAR(); qkt(pA0, pA1, K_lds, qr, r32, hi);
;     finishSM(pB0, pB1, alB, l_reg, pa0, pa1, pa2, pa3); SBAR();
;     if (SDEPTH == 1 || j + 3 < NT) SLOAD(SE, (j + 1 + SDEPTH) * KVBLK); SBAR();
.LBB0_579:
	v_xor_b32_e32 v189, 0x18000, v189
	v_xor_b32_e32 v199, 0x18000, v199
	v_xor_b32_e32 v192, 0x18000, v192
	v_xor_b32_e32 v191, 0x18000, v191
	v_mul_f32_e32 v207, 0xbe0293ee, v206
	v_fmamk_f32 v80, v80, 0x3e0293ee, v207
	v_fmamk_f32 v81, v81, 0x3e0293ee, v207
	v_fmamk_f32 v82, v82, 0x3e0293ee, v207
	v_fmamk_f32 v83, v83, 0x3e0293ee, v207
	v_fmamk_f32 v84, v84, 0x3e0293ee, v207
	v_fmamk_f32 v85, v85, 0x3e0293ee, v207
	v_fmamk_f32 v86, v86, 0x3e0293ee, v207
	v_fmamk_f32 v87, v87, 0x3e0293ee, v207
	v_fmamk_f32 v88, v88, 0x3e0293ee, v207
	v_fmamk_f32 v89, v89, 0x3e0293ee, v207
	v_fmamk_f32 v90, v90, 0x3e0293ee, v207
	v_fmamk_f32 v91, v91, 0x3e0293ee, v207
	v_fmamk_f32 v92, v92, 0x3e0293ee, v207
	v_fmamk_f32 v93, v93, 0x3e0293ee, v207
	v_fmamk_f32 v94, v94, 0x3e0293ee, v207
	v_fmamk_f32 v95, v95, 0x3e0293ee, v207
	v_fmamk_f32 v216, v64, 0x3e0293ee, v207
	v_fmamk_f32 v217, v65, 0x3e0293ee, v207
	v_fmamk_f32 v218, v66, 0x3e0293ee, v207
	v_fmamk_f32 v219, v67, 0x3e0293ee, v207
	v_fmamk_f32 v224, v68, 0x3e0293ee, v207
	v_fmamk_f32 v209, v69, 0x3e0293ee, v207
	v_fmamk_f32 v210, v70, 0x3e0293ee, v207
	v_fmamk_f32 v211, v71, 0x3e0293ee, v207
	v_fmamk_f32 v212, v72, 0x3e0293ee, v207
	v_fmamk_f32 v213, v73, 0x3e0293ee, v207
	v_fmamk_f32 v214, v74, 0x3e0293ee, v207
	v_fmamk_f32 v215, v75, 0x3e0293ee, v207
	v_fmamk_f32 v208, v76, 0x3e0293ee, v207
	v_fmamk_f32 v225, v77, 0x3e0293ee, v207
	v_fmamk_f32 v226, v78, 0x3e0293ee, v207
	v_fmac_f32_e32 v207, 0x3e0293ee, v79
	s_waitcnt lgkmcnt(0)
	s_barrier
	ds_read_b128 v[64:67], v189 offset:32768
	ds_read_b128 v[68:71], v189 offset:40960
	ds_read_b128 v[228:231], v199 offset:32768
	ds_read_b128 v[232:235], v199 offset:40960
	ds_read_b128 v[240:243], v192 offset:32768
	ds_read_b128 v[244:247], v192 offset:40960
	v_exp_f32_e32 v160, v80
	v_exp_f32_e32 v175, v81
	v_exp_f32_e32 v161, v82
	v_exp_f32_e32 v174, v83
	v_exp_f32_e32 v162, v84
	v_exp_f32_e32 v173, v85
	v_exp_f32_e32 v163, v86
	v_exp_f32_e32 v172, v87
	v_exp_f32_e32 v164, v88
	v_exp_f32_e32 v171, v89
	v_exp_f32_e32 v165, v90
	v_exp_f32_e32 v170, v91
	v_exp_f32_e32 v166, v92
	v_exp_f32_e32 v169, v93
	v_exp_f32_e32 v167, v94
	v_exp_f32_e32 v168, v95
	v_exp_f32_e32 v221, v207
	s_waitcnt lgkmcnt(5)
	v_mfma_f32_32x32x16_bf16 v[80:95], v[64:67], v[112:115], 0
	v_add_f32_e32 v207, v175, v160
	v_add_f32_e32 v207, v161, v207
	v_add_f32_e32 v207, v174, v207
	v_add_f32_e32 v207, v162, v207
	v_add_f32_e32 v207, v173, v207
	v_add_f32_e32 v207, v163, v207
	v_add_f32_e32 v207, v172, v207
	s_waitcnt lgkmcnt(4)
	v_mfma_f32_32x32x16_bf16 v[64:79], v[68:71], v[112:115], 0
	v_add_f32_e32 v207, v164, v207
	v_add_f32_e32 v207, v171, v207
	v_add_f32_e32 v207, v165, v207
	v_add_f32_e32 v207, v170, v207
	v_exp_f32_e32 v194, v216
	v_add_f32_e32 v207, v166, v207
	v_exp_f32_e32 v195, v217
	s_waitcnt lgkmcnt(3)
	v_mfma_f32_32x32x16_bf16 v[80:95], v[228:231], v[108:111], v[80:95]
	v_add_f32_e32 v207, v169, v207
	v_exp_f32_e32 v196, v218
	v_add_f32_e32 v207, v167, v207
	v_exp_f32_e32 v197, v219
	v_add_f32_e32 v207, v168, v207
	v_exp_f32_e32 v216, v224
	v_add_f32_e32 v207, v194, v207
	s_waitcnt lgkmcnt(2)
	v_mfma_f32_32x32x16_bf16 v[64:79], v[232:235], v[108:111], v[64:79]
	ds_read_b128 v[228:231], v191 offset:32768
	ds_read_b128 v[232:235], v191 offset:40960
	v_exp_f32_e32 v209, v209
	v_add_f32_e32 v207, v195, v207
	v_exp_f32_e32 v210, v210
	v_add_f32_e32 v207, v196, v207
	v_exp_f32_e32 v211, v211
	v_add_f32_e32 v207, v197, v207
	s_waitcnt lgkmcnt(3)
	v_mfma_f32_32x32x16_bf16 v[80:95], v[240:243], v[120:123], v[80:95]
	v_exp_f32_e32 v212, v212
	v_add_f32_e32 v207, v216, v207
	v_exp_f32_e32 v213, v213
	v_add_f32_e32 v207, v209, v207
	v_exp_f32_e32 v214, v214
	v_add_f32_e32 v207, v210, v207
	v_exp_f32_e32 v215, v215
	s_waitcnt lgkmcnt(2)
	v_mfma_f32_32x32x16_bf16 v[64:79], v[244:247], v[120:123], v[64:79]
	ds_read_b128 v[240:243], v189 offset:32896
	ds_read_b128 v[244:247], v189 offset:41088
	v_add_f32_e32 v207, v211, v207
	v_exp_f32_e32 v217, v208
	v_add_f32_e32 v207, v212, v207
	v_exp_f32_e32 v218, v225
	v_add_f32_e32 v207, v213, v207
	v_exp_f32_e32 v219, v226
	s_waitcnt lgkmcnt(3)
	v_mfma_f32_32x32x16_bf16 v[80:95], v[228:231], v[124:127], v[80:95]
	v_add_f32_e32 v207, v214, v207
	v_add_f32_e32 v207, v215, v207
	v_add_f32_e32 v207, v217, v207
	v_add_f32_e32 v207, v218, v207
	v_add_f32_e32 v207, v219, v207
	v_add_f32_e32 v207, v221, v207
	s_waitcnt lgkmcnt(2)
	v_mfma_f32_32x32x16_bf16 v[64:79], v[232:235], v[124:127], v[64:79]
	ds_read_b128 v[228:231], v199 offset:32896
	ds_read_b128 v[232:235], v199 offset:41088
	s_waitcnt lgkmcnt(3)
	v_mfma_f32_32x32x16_bf16 v[80:95], v[240:243], v[116:119], v[80:95]
	s_waitcnt lgkmcnt(2)
	v_mfma_f32_32x32x16_bf16 v[64:79], v[244:247], v[116:119], v[64:79]
	ds_read_b128 v[240:243], v192 offset:32896
	ds_read_b128 v[244:247], v192 offset:41088
	s_waitcnt lgkmcnt(3)
	v_mfma_f32_32x32x16_bf16 v[80:95], v[228:231], v[104:107], v[80:95]
	s_waitcnt lgkmcnt(2)
	v_mfma_f32_32x32x16_bf16 v[64:79], v[232:235], v[104:107], v[64:79]
	ds_read_b128 v[228:231], v191 offset:32896
	ds_read_b128 v[232:235], v191 offset:41088
	s_waitcnt lgkmcnt(3)
	v_mfma_f32_32x32x16_bf16 v[80:95], v[240:243], v[100:103], v[80:95]
	s_waitcnt lgkmcnt(2)
	v_mfma_f32_32x32x16_bf16 v[64:79], v[244:247], v[100:103], v[64:79]
	v_cvt_pk_bf16_f32 v160, v160, v175
	v_cvt_pk_bf16_f32 v161, v161, v174
	v_cvt_pk_bf16_f32 v162, v162, v173
	v_cvt_pk_bf16_f32 v163, v163, v172
	v_cvt_pk_bf16_f32 v164, v164, v171
	v_cvt_pk_bf16_f32 v165, v165, v170
	s_waitcnt lgkmcnt(1)
	v_mfma_f32_32x32x16_bf16 v[80:95], v[228:231], v[96:99], v[80:95]
	v_cvt_pk_bf16_f32 v166, v166, v169
	v_cvt_pk_bf16_f32 v167, v167, v168
	v_cvt_pk_bf16_f32 v168, v194, v195
	v_cvt_pk_bf16_f32 v169, v196, v197
	v_cvt_pk_bf16_f32 v170, v216, v209
	v_cvt_pk_bf16_f32 v171, v210, v211
	v_cvt_pk_bf16_f32 v172, v212, v213
	s_waitcnt lgkmcnt(0)
	v_mfma_f32_32x32x16_bf16 v[64:79], v[232:235], v[96:99], v[64:79]
	v_cvt_pk_bf16_f32 v173, v214, v215
	v_cvt_pk_bf16_f32 v174, v217, v218
	v_cvt_pk_bf16_f32 v175, v219, v221
	s_add_i32 s50, s50, 2
	s_cmp_ge_u32 s50, s49
	s_cselect_b64 s[44:45], -1, 0
	s_and_b64 vcc, exec, s[44:45]
	s_cbranch_vccnz .Lattn_skip_loads
	global_load_dwordx4 v[128:131], v176, s[52:53]
	global_load_dwordx4 v[132:135], v176, s[52:53] offset:-512
	s_add_u32 s52, s52, 0x18000
	s_addc_u32 s53, s53, 0
	global_load_dwordx4 v[136:139], v176, s[52:53]
	global_load_dwordx4 v[140:143], v176, s[52:53] offset:-512
	s_add_u32 s52, s52, 0x18000
	s_addc_u32 s53, s53, 0
